# L2 prefetch of next q/k chunk rows by one wave in both scans; lr projection rewritten (all WGs, K split over wave pairs, 32 loads in flight) and moved after the in-proj GEMM; WA touched before P7
# speedup vs baseline: 1.0315x; 1.0249x over previous
.LBB0_250:
	v_mov_b32_e32 v4, v3
	v_mov_b32_e32 v5, v3
	v_mov_b32_e32 v100, v3
	v_mov_b32_e32 v101, v3
	v_lshl_add_u64 v[146:147], v[2:3], 1, s[56:57]
	s_lshl_b32 s22, s25, 9
	s_lshl_b32 s23, s60, 6
	v_mov_b32_e32 v2, v3
	v_mov_b32_e32 v98, v3
	v_mov_b32_e32 v99, v3
	v_mov_b64_e32 v[132:133], v[100:101]
	v_mov_b64_e32 v[104:105], v[100:101]
	v_mov_b64_e32 v[136:137], v[100:101]
	v_mov_b64_e32 v[108:109], v[100:101]
	v_mov_b64_e32 v[120:121], v[100:101]
	v_mov_b64_e32 v[112:113], v[100:101]
	v_mov_b64_e32 v[116:117], v[100:101]
	v_mov_b64_e32 v[80:81], v[4:5]
	s_add_i32 s22, s22, s0
	v_lshl_add_u32 v165, s60, 7, v207
	v_lshl_add_u32 v166, s60, 8, v206
	s_mov_b32 s74, 0
	s_lshl_b32 s23, s23, 2
	v_mov_b64_e32 v[130:131], v[98:99]
	v_mov_b64_e32 v[102:103], v[98:99]
	v_mov_b64_e32 v[134:135], v[98:99]
	v_mov_b64_e32 v[106:107], v[98:99]
	v_mov_b64_e32 v[118:119], v[98:99]
	v_mov_b64_e32 v[110:111], v[98:99]
	v_mov_b64_e32 v[114:115], v[98:99]
	v_mov_b64_e32 v[78:79], v[2:3]
	v_and_b32_e32 v240, 63, v151
	v_bfe_u32 v241, v240, 3, 2
	s_lshr_b32 s98, s92, 3
	s_and_b32 s98, s98, 15
	s_lshl_b32 s98, s98, 2
	v_add_u32_e32 v241, s98, v241
	v_mul_u32_u24_e32 v241, 0x6080, v241
	v_and_b32_e32 v242, 3, v240
	v_lshlrev_b32_e32 v242, 7, v242
	v_bfe_u32 v243, v240, 2, 1
	v_lshlrev_b32_e32 v243, 11, v243
	s_mul_i32 s99, s0, 512
	v_add3_u32 v240, v241, v242, v243
	v_add_u32_e32 v240, s99, v240
	s_branch .LBB0_252

.LBB0_252:
	s_min_u32 s75, s74, 0x7d
	s_add_i32 s75, s75, 2
	s_lshl_b32 s26, s75, 6
	s_add_i32 s26, s26, s94
	v_mad_i64_i32 v[4:5], s[26:27], s26, v230, v[146:147]
	s_waitcnt vmcnt(8)
	v_add_co_u32_e32 v82, vcc, s81, v4
	s_waitcnt lgkmcnt(0)
	s_barrier
	s_nop 0
	v_addc_co_u32_e32 v83, vcc, 0, v5, vcc
	global_load_dwordx4 v[142:145], v[4:5], off
	global_load_dwordx4 v[138:141], v[82:83], off offset:256
	v_add_co_u32_e32 v82, vcc, s82, v4
	s_nop 1
	v_addc_co_u32_e32 v83, vcc, 0, v5, vcc
	v_add_co_u32_e32 v84, vcc, s83, v4
	s_nop 1
	v_addc_co_u32_e32 v85, vcc, 0, v5, vcc
	global_load_dwordx4 v[126:129], v[82:83], off offset:512
	global_load_dwordx4 v[122:125], v[84:85], off offset:768
	v_add_co_u32_e32 v82, vcc, s84, v4
	s_nop 1
	v_addc_co_u32_e32 v83, vcc, 0, v5, vcc
	v_add_co_u32_e32 v84, vcc, 0x3c000, v4
	s_nop 1
	v_addc_co_u32_e32 v85, vcc, 0, v5, vcc
	global_load_dwordx4 v[94:97], v[82:83], off offset:1024
	global_load_dwordx4 v[90:93], v[84:85], off offset:1280
	v_add_co_u32_e32 v82, vcc, 0x48000, v4
	s_nop 1
	v_addc_co_u32_e32 v83, vcc, 0, v5, vcc
	v_add_co_u32_e32 v4, vcc, 0x54000, v4
	s_nop 1
	v_addc_co_u32_e32 v5, vcc, 0, v5, vcc
	global_load_dwordx4 v[86:89], v[82:83], off offset:1536
	s_nop 0
	global_load_dwordx4 v[82:85], v[4:5], off offset:1792
	s_and_b64 vcc, exec, s[16:17]
	s_cbranch_vccnz .LBB0_254
	s_lshl_b32 s26, s75, 2
	s_add_i32 s26, s26, s22
	s_ashr_i32 s27, s26, 31
	s_lshl_b64 s[26:27], s[26:27], 10
	v_lshl_add_u64 v[4:5], v[158:159], 0, s[26:27]
	global_load_dwordx4 v[78:81], v[4:5], off
	s_min_u32 s99, s74, 0x7d
	s_add_i32 s99, s99, 4
	s_min_u32 s99, s99, 0x7f
	s_lshl_b32 s99, s99, 6
	s_add_i32 s99, s99, s94
	s_mul_hi_u32 s101, s99, 0x6080
	s_mul_i32 s100, s99, 0x6080
	s_add_u32 s100, s100, s56
	s_addc_u32 s101, s101, s57
	global_load_dword v241, v240, s[100:101]

.LBB0_256:
	s_min_u32 s97, s74, 0x7c
	s_add_i32 s97, s97, 3
	s_lshl_b32 s26, s97, 6
	s_add_i32 s26, s26, s94
	v_mad_i64_i32 v[18:19], s[26:27], s26, v230, v[146:147]
	v_add_co_u32_e32 v20, vcc, 0xc000, v18
	s_waitcnt lgkmcnt(0)
	s_barrier
	s_nop 0
	v_addc_co_u32_e32 v21, vcc, 0, v19, vcc
	global_load_dwordx4 v[50:53], v[18:19], off
	global_load_dwordx4 v[54:57], v[20:21], off offset:256
	v_add_co_u32_e32 v20, vcc, 0x18000, v18
	s_nop 1
	v_addc_co_u32_e32 v21, vcc, 0, v19, vcc
	v_add_co_u32_e32 v22, vcc, 0x24000, v18
	s_nop 1
	v_addc_co_u32_e32 v23, vcc, 0, v19, vcc
	global_load_dwordx4 v[38:41], v[20:21], off offset:512
	global_load_dwordx4 v[42:45], v[22:23], off offset:768
	v_add_co_u32_e32 v20, vcc, 0x30000, v18
	s_nop 1
	v_addc_co_u32_e32 v21, vcc, 0, v19, vcc
	v_add_co_u32_e32 v22, vcc, 0x3c000, v18
	s_nop 1
	v_addc_co_u32_e32 v23, vcc, 0, v19, vcc
	global_load_dwordx4 v[26:29], v[20:21], off offset:1024
	global_load_dwordx4 v[30:33], v[22:23], off offset:1280
	v_add_co_u32_e32 v20, vcc, 0x48000, v18
	s_nop 1
	v_addc_co_u32_e32 v21, vcc, 0, v19, vcc
	v_add_co_u32_e32 v22, vcc, 0x54000, v18
	s_nop 1
	v_addc_co_u32_e32 v23, vcc, 0, v19, vcc
	global_load_dwordx4 v[18:21], v[20:21], off offset:1536
	s_nop 0
	global_load_dwordx4 v[22:25], v[22:23], off offset:1792
	s_and_b64 vcc, exec, s[16:17]
	s_cbranch_vccnz .LBB0_258
	s_lshl_b32 s26, s97, 2
	s_add_i32 s26, s26, s22
	s_ashr_i32 s27, s26, 31
	s_lshl_b64 s[26:27], s[26:27], 10
	v_lshl_add_u64 v[6:7], v[158:159], 0, s[26:27]
	global_load_dwordx4 v[6:9], v[6:7], off
	s_min_u32 s99, s74, 0x7c
	s_add_i32 s99, s99, 5
	s_min_u32 s99, s99, 0x7f
	s_lshl_b32 s99, s99, 6
	s_add_i32 s99, s99, s94
	s_mul_hi_u32 s101, s99, 0x6080
	s_mul_i32 s100, s99, 0x6080
	s_add_u32 s100, s100, s56
	s_addc_u32 s101, s101, s57
	global_load_dword v241, v240, s[100:101]

.LBB0_260:
	s_cmpk_gt_u32 s74, 0x7d
	s_cbranch_scc1 .LBB0_251
	s_min_u32 s86, s74, 0x7b
	s_add_i32 s86, s86, 4
	s_lshl_b32 s26, s86, 6
	s_add_i32 s26, s26, s94
	v_mad_i64_i32 v[70:71], s[26:27], s26, v230, v[146:147]
	v_add_co_u32_e32 v14, vcc, 0xc000, v70
	s_waitcnt lgkmcnt(0)
	s_barrier
	s_nop 0
	v_addc_co_u32_e32 v15, vcc, 0, v71, vcc
	v_add_co_u32_e32 v34, vcc, 0x18000, v70
	global_load_dwordx4 v[10:13], v[70:71], off
	s_nop 0
	global_load_dwordx4 v[14:17], v[14:15], off offset:256
	v_addc_co_u32_e32 v35, vcc, 0, v71, vcc
	v_add_co_u32_e32 v46, vcc, 0x24000, v70
	s_nop 1
	v_addc_co_u32_e32 v47, vcc, 0, v71, vcc
	v_add_co_u32_e32 v62, vcc, 0x30000, v70
	global_load_dwordx4 v[34:37], v[34:35], off offset:512
	s_nop 0
	global_load_dwordx4 v[46:49], v[46:47], off offset:768
	v_addc_co_u32_e32 v63, vcc, 0, v71, vcc
	v_add_co_u32_e32 v66, vcc, 0x3c000, v70
	s_nop 1
	v_addc_co_u32_e32 v67, vcc, 0, v71, vcc
	v_add_co_u32_e32 v72, vcc, 0x48000, v70
	global_load_dwordx4 v[62:65], v[62:63], off offset:1024
	s_nop 0
	global_load_dwordx4 v[66:69], v[66:67], off offset:1280
	v_addc_co_u32_e32 v73, vcc, 0, v71, vcc
	v_add_co_u32_e32 v74, vcc, 0x54000, v70
	s_nop 1
	v_addc_co_u32_e32 v75, vcc, 0, v71, vcc
	global_load_dwordx4 v[70:73], v[72:73], off offset:1536
	s_nop 0
	global_load_dwordx4 v[74:77], v[74:75], off offset:1792
	s_and_b64 vcc, exec, s[16:17]
	s_cbranch_vccnz .LBB0_263
	s_lshl_b32 s26, s86, 2
	s_add_i32 s26, s26, s22
	s_ashr_i32 s27, s26, 31
	s_lshl_b64 s[26:27], s[26:27], 10
	v_lshl_add_u64 v[58:59], v[158:159], 0, s[26:27]
	global_load_dwordx4 v[58:61], v[58:59], off
	s_min_u32 s99, s74, 0x7b
	s_add_i32 s99, s99, 6
	s_min_u32 s99, s99, 0x7f
	s_lshl_b32 s99, s99, 6
	s_add_i32 s99, s99, s94
	s_mul_hi_u32 s101, s99, 0x6080
	s_mul_i32 s100, s99, 0x6080
	s_add_u32 s100, s100, s56
	s_addc_u32 s101, s101, s57
	global_load_dword v241, v240, s[100:101]

.LBB0_552:
	s_cmpk_lg_i32 s68, 0x100
	s_cbranch_scc1 .Llr_orig
	v_mov_b32_e32 v0, v188
	s_nop 0
	v_readfirstlane_b32 s2, v0
	v_and_b32_e32 v1, 63, v0
	s_lshr_b32 s2, s2, 6
	s_and_b32 s3, s2, 3
	s_lshr_b32 s4, s2, 2
	s_lshl_b32 s5, s30, 2
	s_add_i32 s5, s5, s3
	v_and_b32_e32 v2, 15, v1
	v_lshrrev_b32_e32 v3, 4, v1
	v_lshlrev_b32_e32 v136, 12, v2
	v_lshl_add_u32 v136, v3, 4, v136
	s_lshl_b32 s98, s4, 11
	v_add_u32_e32 v137, s98, v136
	s_lshl_b32 s99, s5, 16
	v_add_u32_e32 v136, s99, v137
	s_add_u32 s100, s50, 0x200000
	s_addc_u32 s101, s51, 0
	v_mov_b32_e32 v4, 0
	v_mov_b32_e32 v5, 0
	v_mov_b32_e32 v6, 0
	v_mov_b32_e32 v7, 0
	global_load_dwordx4 v[8:11], v136, s[58:59]
	global_load_dwordx4 v[12:15], v137, s[100:101]
	global_load_dwordx4 v[16:19], v136, s[58:59] offset:64
	global_load_dwordx4 v[20:23], v137, s[100:101] offset:64
	global_load_dwordx4 v[24:27], v136, s[58:59] offset:128
	global_load_dwordx4 v[28:31], v137, s[100:101] offset:128
	global_load_dwordx4 v[32:35], v136, s[58:59] offset:192
	global_load_dwordx4 v[36:39], v137, s[100:101] offset:192
	global_load_dwordx4 v[40:43], v136, s[58:59] offset:256
	global_load_dwordx4 v[44:47], v137, s[100:101] offset:256
	global_load_dwordx4 v[48:51], v136, s[58:59] offset:320
	global_load_dwordx4 v[52:55], v137, s[100:101] offset:320
	global_load_dwordx4 v[56:59], v136, s[58:59] offset:384
	global_load_dwordx4 v[60:63], v137, s[100:101] offset:384
	global_load_dwordx4 v[64:67], v136, s[58:59] offset:448
	global_load_dwordx4 v[68:71], v137, s[100:101] offset:448
	global_load_dwordx4 v[72:75], v136, s[58:59] offset:512
	global_load_dwordx4 v[76:79], v137, s[100:101] offset:512
	global_load_dwordx4 v[80:83], v136, s[58:59] offset:576
	global_load_dwordx4 v[84:87], v137, s[100:101] offset:576
	global_load_dwordx4 v[88:91], v136, s[58:59] offset:640
	global_load_dwordx4 v[92:95], v137, s[100:101] offset:640
	global_load_dwordx4 v[96:99], v136, s[58:59] offset:704
	global_load_dwordx4 v[100:103], v137, s[100:101] offset:704
	global_load_dwordx4 v[104:107], v136, s[58:59] offset:768
	global_load_dwordx4 v[108:111], v137, s[100:101] offset:768
	global_load_dwordx4 v[112:115], v136, s[58:59] offset:832
	global_load_dwordx4 v[116:119], v137, s[100:101] offset:832
	global_load_dwordx4 v[120:123], v136, s[58:59] offset:896
	global_load_dwordx4 v[124:127], v137, s[100:101] offset:896
	global_load_dwordx4 v[128:131], v136, s[58:59] offset:960
	global_load_dwordx4 v[132:135], v137, s[100:101] offset:960
	s_waitcnt vmcnt(30)
	v_mfma_f32_16x16x32_bf16 v[4:7], v[8:11], v[12:15], v[4:7]
	global_load_dwordx4 v[8:11], v136, s[58:59] offset:1024
	global_load_dwordx4 v[12:15], v137, s[100:101] offset:1024
	s_waitcnt vmcnt(30)
	v_mfma_f32_16x16x32_bf16 v[4:7], v[16:19], v[20:23], v[4:7]
	global_load_dwordx4 v[16:19], v136, s[58:59] offset:1088
	global_load_dwordx4 v[20:23], v137, s[100:101] offset:1088
	s_waitcnt vmcnt(30)
	v_mfma_f32_16x16x32_bf16 v[4:7], v[24:27], v[28:31], v[4:7]
	global_load_dwordx4 v[24:27], v136, s[58:59] offset:1152
	global_load_dwordx4 v[28:31], v137, s[100:101] offset:1152
	s_waitcnt vmcnt(30)
	v_mfma_f32_16x16x32_bf16 v[4:7], v[32:35], v[36:39], v[4:7]
	global_load_dwordx4 v[32:35], v136, s[58:59] offset:1216
	global_load_dwordx4 v[36:39], v137, s[100:101] offset:1216
	s_waitcnt vmcnt(30)
	v_mfma_f32_16x16x32_bf16 v[4:7], v[40:43], v[44:47], v[4:7]
	global_load_dwordx4 v[40:43], v136, s[58:59] offset:1280
	global_load_dwordx4 v[44:47], v137, s[100:101] offset:1280
	s_waitcnt vmcnt(30)
	v_mfma_f32_16x16x32_bf16 v[4:7], v[48:51], v[52:55], v[4:7]
	global_load_dwordx4 v[48:51], v136, s[58:59] offset:1344
	global_load_dwordx4 v[52:55], v137, s[100:101] offset:1344
	s_waitcnt vmcnt(30)
	v_mfma_f32_16x16x32_bf16 v[4:7], v[56:59], v[60:63], v[4:7]
	global_load_dwordx4 v[56:59], v136, s[58:59] offset:1408
	global_load_dwordx4 v[60:63], v137, s[100:101] offset:1408
	s_waitcnt vmcnt(30)
	v_mfma_f32_16x16x32_bf16 v[4:7], v[64:67], v[68:71], v[4:7]
	global_load_dwordx4 v[64:67], v136, s[58:59] offset:1472
	global_load_dwordx4 v[68:71], v137, s[100:101] offset:1472
	s_waitcnt vmcnt(30)
	v_mfma_f32_16x16x32_bf16 v[4:7], v[72:75], v[76:79], v[4:7]
	global_load_dwordx4 v[72:75], v136, s[58:59] offset:1536
	global_load_dwordx4 v[76:79], v137, s[100:101] offset:1536
	s_waitcnt vmcnt(30)
	v_mfma_f32_16x16x32_bf16 v[4:7], v[80:83], v[84:87], v[4:7]
	global_load_dwordx4 v[80:83], v136, s[58:59] offset:1600
	global_load_dwordx4 v[84:87], v137, s[100:101] offset:1600
	s_waitcnt vmcnt(30)
	v_mfma_f32_16x16x32_bf16 v[4:7], v[88:91], v[92:95], v[4:7]
	global_load_dwordx4 v[88:91], v136, s[58:59] offset:1664
	global_load_dwordx4 v[92:95], v137, s[100:101] offset:1664
	s_waitcnt vmcnt(30)
	v_mfma_f32_16x16x32_bf16 v[4:7], v[96:99], v[100:103], v[4:7]
	global_load_dwordx4 v[96:99], v136, s[58:59] offset:1728
	global_load_dwordx4 v[100:103], v137, s[100:101] offset:1728
	s_waitcnt vmcnt(30)
	v_mfma_f32_16x16x32_bf16 v[4:7], v[104:107], v[108:111], v[4:7]
	global_load_dwordx4 v[104:107], v136, s[58:59] offset:1792
	global_load_dwordx4 v[108:111], v137, s[100:101] offset:1792
	s_waitcnt vmcnt(30)
	v_mfma_f32_16x16x32_bf16 v[4:7], v[112:115], v[116:119], v[4:7]
	global_load_dwordx4 v[112:115], v136, s[58:59] offset:1856
	global_load_dwordx4 v[116:119], v137, s[100:101] offset:1856
	s_waitcnt vmcnt(30)
	v_mfma_f32_16x16x32_bf16 v[4:7], v[120:123], v[124:127], v[4:7]
	global_load_dwordx4 v[120:123], v136, s[58:59] offset:1920
	global_load_dwordx4 v[124:127], v137, s[100:101] offset:1920
	s_waitcnt vmcnt(30)
	v_mfma_f32_16x16x32_bf16 v[4:7], v[128:131], v[132:135], v[4:7]
	global_load_dwordx4 v[128:131], v136, s[58:59] offset:1984
	global_load_dwordx4 v[132:135], v137, s[100:101] offset:1984
	s_waitcnt vmcnt(30)
	v_mfma_f32_16x16x32_bf16 v[4:7], v[8:11], v[12:15], v[4:7]
	s_waitcnt vmcnt(28)
	v_mfma_f32_16x16x32_bf16 v[4:7], v[16:19], v[20:23], v[4:7]
	s_waitcnt vmcnt(26)
	v_mfma_f32_16x16x32_bf16 v[4:7], v[24:27], v[28:31], v[4:7]
	s_waitcnt vmcnt(24)
	v_mfma_f32_16x16x32_bf16 v[4:7], v[32:35], v[36:39], v[4:7]
	s_waitcnt vmcnt(22)
	v_mfma_f32_16x16x32_bf16 v[4:7], v[40:43], v[44:47], v[4:7]
	s_waitcnt vmcnt(20)
	v_mfma_f32_16x16x32_bf16 v[4:7], v[48:51], v[52:55], v[4:7]
	s_waitcnt vmcnt(18)
	v_mfma_f32_16x16x32_bf16 v[4:7], v[56:59], v[60:63], v[4:7]
	s_waitcnt vmcnt(16)
	v_mfma_f32_16x16x32_bf16 v[4:7], v[64:67], v[68:71], v[4:7]
	s_waitcnt vmcnt(14)
	v_mfma_f32_16x16x32_bf16 v[4:7], v[72:75], v[76:79], v[4:7]
	s_waitcnt vmcnt(12)
	v_mfma_f32_16x16x32_bf16 v[4:7], v[80:83], v[84:87], v[4:7]
	s_waitcnt vmcnt(10)
	v_mfma_f32_16x16x32_bf16 v[4:7], v[88:91], v[92:95], v[4:7]
	s_waitcnt vmcnt(8)
	v_mfma_f32_16x16x32_bf16 v[4:7], v[96:99], v[100:103], v[4:7]
	s_waitcnt vmcnt(6)
	v_mfma_f32_16x16x32_bf16 v[4:7], v[104:107], v[108:111], v[4:7]
	s_waitcnt vmcnt(4)
	v_mfma_f32_16x16x32_bf16 v[4:7], v[112:115], v[116:119], v[4:7]
	s_waitcnt vmcnt(2)
	v_mfma_f32_16x16x32_bf16 v[4:7], v[120:123], v[124:127], v[4:7]
	s_waitcnt vmcnt(0)
	v_mfma_f32_16x16x32_bf16 v[4:7], v[128:131], v[132:135], v[4:7]
	s_nop 7
	s_nop 1
	v_lshlrev_b32_e32 v8, 4, v1
	s_lshl_b32 s98, s3, 10
	v_add_u32_e32 v8, s98, v8
	s_cmp_lt_u32 s2, 4
	s_cbranch_scc1 .Llrn_lo1
	ds_write_b128 v8, v[4:7]
.Llrn_lo1:
	s_waitcnt lgkmcnt(0)
	s_barrier
	s_cmp_lt_u32 s2, 4
	s_cbranch_scc0 .Llrn_done
	ds_read_b128 v[12:15], v8
	v_lshlrev_b32_e32 v9, 2, v2
	v_lshl_add_u32 v9, v3, 8, v9
	s_lshl_b32 s98, s5, 10
	v_add_u32_e32 v9, s98, v9
	s_waitcnt lgkmcnt(0)
	v_add_f32_e32 v4, v4, v12
	v_add_f32_e32 v5, v5, v13
	v_add_f32_e32 v6, v6, v14
	v_add_f32_e32 v7, v7, v15
	global_store_dword v9, v4, s[0:1]
	global_store_dword v9, v5, s[0:1] offset:64
	global_store_dword v9, v6, s[0:1] offset:128
	global_store_dword v9, v7, s[0:1] offset:192
.Llrn_done:
	s_branch .Llr_done

.LBB0_692:
	v_mov_b32_e32 v2, v1
	v_mov_b32_e32 v3, v1
	v_mov_b32_e32 v94, v1
	v_mov_b32_e32 v95, v1
	v_lshl_add_u64 v[144:145], v[0:1], 1, s[56:57]
	s_lshl_b32 s10, s13, 10
	s_lshl_b32 s11, s14, 6
	v_mov_b32_e32 v0, v1
	v_mov_b32_e32 v92, v1
	v_mov_b32_e32 v93, v1
	v_mov_b64_e32 v[130:131], v[94:95]
	v_mov_b64_e32 v[102:103], v[94:95]
	v_mov_b64_e32 v[134:135], v[94:95]
	v_mov_b64_e32 v[106:107], v[94:95]
	v_mov_b64_e32 v[118:119], v[94:95]
	v_mov_b64_e32 v[114:115], v[94:95]
	v_mov_b64_e32 v[110:111], v[94:95]
	v_mov_b64_e32 v[78:79], v[2:3]
	s_add_i32 s10, s10, s35
	v_lshl_add_u32 v149, s14, 7, v179
	v_lshl_add_u32 v150, s14, 8, v178
	s_mov_b32 s38, 0
	s_lshl_b32 s11, s11, 2
	v_mov_b64_e32 v[128:129], v[92:93]
	v_mov_b64_e32 v[100:101], v[92:93]
	v_mov_b64_e32 v[132:133], v[92:93]
	v_mov_b64_e32 v[104:105], v[92:93]
	v_mov_b64_e32 v[116:117], v[92:93]
	v_mov_b64_e32 v[112:113], v[92:93]
	v_mov_b64_e32 v[108:109], v[92:93]
	v_mov_b64_e32 v[76:77], v[0:1]
	v_and_b32_e32 v201, 63, v170
	v_bfe_u32 v202, v201, 3, 2
	s_bfe_u32 s98, s27, 0x40003
	s_and_b32 s98, s98, 15
	s_lshl_b32 s98, s98, 2
	v_add_u32_e32 v202, s98, v202
	v_mul_u32_u24_e32 v202, 0x6080, v202
	v_and_b32_e32 v203, 3, v201
	v_lshlrev_b32_e32 v203, 7, v203
	v_bfe_u32 v204, v201, 2, 1
	v_lshlrev_b32_e32 v204, 12, v204
	s_mul_i32 s99, s35, 512
	v_add3_u32 v201, v202, v203, v204
	v_add_u32_e32 v201, s99, v201
	s_branch .LBB0_694

.LBB0_694:
	s_min_u32 s39, s38, 0x7d
	s_add_i32 s39, s39, 2
	s_lshl_b32 s40, s39, 6
	s_add_i32 s40, s40, s37
	v_mad_i64_i32 v[2:3], s[40:41], s40, v194, v[144:145]
	s_waitcnt vmcnt(8)
	v_add_co_u32_e32 v80, vcc, s18, v2
	s_waitcnt lgkmcnt(0)
	s_barrier
	s_nop 0
	v_addc_co_u32_e32 v81, vcc, 0, v3, vcc
	global_load_dwordx4 v[140:143], v[2:3], off
	global_load_dwordx4 v[136:139], v[80:81], off offset:256
	v_add_co_u32_e32 v80, vcc, s19, v2
	s_nop 1
	v_addc_co_u32_e32 v81, vcc, 0, v3, vcc
	v_add_co_u32_e32 v82, vcc, s20, v2
	s_nop 1
	v_addc_co_u32_e32 v83, vcc, 0, v3, vcc
	global_load_dwordx4 v[124:127], v[80:81], off offset:512
	global_load_dwordx4 v[120:123], v[82:83], off offset:768
	v_add_co_u32_e32 v80, vcc, s21, v2
	s_nop 1
	v_addc_co_u32_e32 v81, vcc, 0, v3, vcc
	v_add_co_u32_e32 v82, vcc, 0x3c000, v2
	s_nop 1
	v_addc_co_u32_e32 v83, vcc, 0, v3, vcc
	global_load_dwordx4 v[96:99], v[80:81], off offset:1024
	global_load_dwordx4 v[88:91], v[82:83], off offset:1280
	v_add_co_u32_e32 v80, vcc, 0x48000, v2
	s_nop 1
	v_addc_co_u32_e32 v81, vcc, 0, v3, vcc
	v_add_co_u32_e32 v2, vcc, 0x54000, v2
	s_nop 1
	v_addc_co_u32_e32 v3, vcc, 0, v3, vcc
	global_load_dwordx4 v[84:87], v[80:81], off offset:1536
	s_nop 0
	global_load_dwordx4 v[80:83], v[2:3], off offset:1792
	s_and_b64 vcc, exec, s[6:7]
	s_cbranch_vccnz .LBB0_696
	s_lshl_b32 s39, s39, 3
	s_add_i32 s40, s39, s10
	s_ashr_i32 s41, s40, 31
	s_lshl_b64 s[40:41], s[40:41], 10
	v_lshl_add_u64 v[2:3], v[146:147], 0, s[40:41]
	global_load_dwordx4 v[76:79], v[2:3], off
	s_min_u32 s99, s38, 0x7d
	s_add_i32 s99, s99, 4
	s_min_u32 s99, s99, 0x7f
	s_lshl_b32 s99, s99, 6
	s_add_i32 s99, s99, s37
	s_mul_hi_u32 s101, s99, 0x6080
	s_mul_i32 s100, s99, 0x6080
	s_add_u32 s100, s100, s56
	s_addc_u32 s101, s101, s57
	global_load_dword v202, v201, s[100:101]

.LBB0_698:
	s_min_u32 s43, s38, 0x7c
	s_add_i32 s43, s43, 3
	s_lshl_b32 s44, s43, 6
	s_add_i32 s44, s44, s37
	v_mad_i64_i32 v[16:17], s[44:45], s44, v194, v[144:145]
	v_add_co_u32_e32 v18, vcc, 0xc000, v16
	s_waitcnt lgkmcnt(0)
	s_barrier
	s_nop 0
	v_addc_co_u32_e32 v19, vcc, 0, v17, vcc
	global_load_dwordx4 v[48:51], v[16:17], off
	global_load_dwordx4 v[52:55], v[18:19], off offset:256
	v_add_co_u32_e32 v18, vcc, 0x18000, v16
	s_nop 1
	v_addc_co_u32_e32 v19, vcc, 0, v17, vcc
	v_add_co_u32_e32 v20, vcc, 0x24000, v16
	s_nop 1
	v_addc_co_u32_e32 v21, vcc, 0, v17, vcc
	global_load_dwordx4 v[40:43], v[18:19], off offset:512
	global_load_dwordx4 v[44:47], v[20:21], off offset:768
	v_add_co_u32_e32 v18, vcc, 0x30000, v16
	s_nop 1
	v_addc_co_u32_e32 v19, vcc, 0, v17, vcc
	v_add_co_u32_e32 v20, vcc, 0x3c000, v16
	s_nop 1
	v_addc_co_u32_e32 v21, vcc, 0, v17, vcc
	global_load_dwordx4 v[28:31], v[18:19], off offset:1024
	global_load_dwordx4 v[32:35], v[20:21], off offset:1280
	v_add_co_u32_e32 v18, vcc, 0x48000, v16
	s_nop 1
	v_addc_co_u32_e32 v19, vcc, 0, v17, vcc
	v_add_co_u32_e32 v20, vcc, 0x54000, v16
	s_nop 1
	v_addc_co_u32_e32 v21, vcc, 0, v17, vcc
	global_load_dwordx4 v[16:19], v[18:19], off offset:1536
	s_nop 0
	global_load_dwordx4 v[20:23], v[20:21], off offset:1792
	s_and_b64 vcc, exec, s[6:7]
	s_cbranch_vccnz .LBB0_700
	s_lshl_b32 s43, s43, 3
	s_add_i32 s44, s43, s10
	s_ashr_i32 s45, s44, 31
	s_lshl_b64 s[44:45], s[44:45], 10
	v_lshl_add_u64 v[4:5], v[146:147], 0, s[44:45]
	global_load_dwordx4 v[4:7], v[4:5], off
	s_min_u32 s99, s38, 0x7c
	s_add_i32 s99, s99, 5
	s_min_u32 s99, s99, 0x7f
	s_lshl_b32 s99, s99, 6
	s_add_i32 s99, s99, s37
	s_mul_hi_u32 s101, s99, 0x6080
	s_mul_i32 s100, s99, 0x6080
	s_add_u32 s100, s100, s56
	s_addc_u32 s101, s101, s57
	global_load_dword v202, v201, s[100:101]

.LBB0_702:
	s_cmpk_gt_u32 s38, 0x7d
	s_cbranch_scc1 .LBB0_693
	s_min_u32 s40, s38, 0x7b
	s_add_i32 s40, s40, 4
	s_lshl_b32 s41, s40, 6
	s_add_i32 s41, s41, s37
	v_mad_i64_i32 v[68:69], s[42:43], s41, v194, v[144:145]
	v_add_co_u32_e32 v12, vcc, 0xc000, v68
	s_waitcnt lgkmcnt(0)
	s_barrier
	s_nop 0
	v_addc_co_u32_e32 v13, vcc, 0, v69, vcc
	v_add_co_u32_e32 v24, vcc, 0x18000, v68
	global_load_dwordx4 v[8:11], v[68:69], off
	s_nop 0
	global_load_dwordx4 v[12:15], v[12:13], off offset:256
	v_addc_co_u32_e32 v25, vcc, 0, v69, vcc
	v_add_co_u32_e32 v36, vcc, 0x24000, v68
	s_nop 1
	v_addc_co_u32_e32 v37, vcc, 0, v69, vcc
	v_add_co_u32_e32 v56, vcc, 0x30000, v68
	global_load_dwordx4 v[24:27], v[24:25], off offset:512
	s_nop 0
	global_load_dwordx4 v[36:39], v[36:37], off offset:768
	v_addc_co_u32_e32 v57, vcc, 0, v69, vcc
	v_add_co_u32_e32 v64, vcc, 0x3c000, v68
	s_nop 1
	v_addc_co_u32_e32 v65, vcc, 0, v69, vcc
	v_add_co_u32_e32 v70, vcc, 0x48000, v68
	global_load_dwordx4 v[56:59], v[56:57], off offset:1024
	s_nop 0
	global_load_dwordx4 v[64:67], v[64:65], off offset:1280
	v_addc_co_u32_e32 v71, vcc, 0, v69, vcc
	v_add_co_u32_e32 v72, vcc, 0x54000, v68
	s_nop 1
	v_addc_co_u32_e32 v73, vcc, 0, v69, vcc
	global_load_dwordx4 v[68:71], v[70:71], off offset:1536
	s_nop 0
	global_load_dwordx4 v[72:75], v[72:73], off offset:1792
	s_and_b64 vcc, exec, s[6:7]
	s_cbranch_vccnz .LBB0_705
	s_lshl_b32 s40, s40, 3
	s_add_i32 s40, s40, s10
	s_ashr_i32 s41, s40, 31
	s_lshl_b64 s[40:41], s[40:41], 10
	v_lshl_add_u64 v[60:61], v[146:147], 0, s[40:41]
	global_load_dwordx4 v[60:63], v[60:61], off
	s_min_u32 s99, s38, 0x7b
	s_add_i32 s99, s99, 6
	s_min_u32 s99, s99, 0x7f
	s_lshl_b32 s99, s99, 6
	s_add_i32 s99, s99, s37
	s_mul_hi_u32 s101, s99, 0x6080
	s_mul_i32 s100, s99, 0x6080
	s_add_u32 s100, s100, s56
	s_addc_u32 s101, s101, s57
	global_load_dword v202, v201, s[100:101]
